# adds hand-written fast path for the c_q/c_kv RMSNorm rescale loop (4 rows per group, 16 loads in flight, no store drains)
# speedup vs baseline: 1.0551x; 1.0072x over previous
; __device__ __forceinline__ unsigned pk2(float lo, float hi) { return pg8::cvt_pk_bf16(lo, hi); }
; __global__ void __launch_bounds__(512, 2) fwd_megakernel(Params p) {
;     ...
;     if constexpr (PH_MASK & 16) {
;         FRESH_LANE_IDS;
;         for (int m = gw; m < T; m += NGW) {
;             const float rq = rsqrtf(ssq_cq[m] * (1.0f / 384.0f) + EPS), rk = rsqrtf(ssq_ckv[m] * (1.0f / 256.0f) + EPS);
;             if (lane < 48) { u32x4* pq = (u32x4*)(cqg + (size_t)m * 384) + lane; u32x4 v = *pq;
; #pragma unroll
;                 for (int q = 0; q < 4; ++q) v[q] = pk2(__uint_as_float(v[q] << 16) * rq, __uint_as_float(v[q] & 0xffff0000u) * rq);
;                 *pq = v; }
;             if (lane < 32) { u32x4* pk = (u32x4*)(ckvg + (size_t)m * 256) + lane; u32x4 v = *pk;
; #pragma unroll
;                 for (int q = 0; q < 4; ++q) v[q] = pk2(__uint_as_float(v[q] << 16) * rk, __uint_as_float(v[q] & 0xffff0000u) * rk);
;                 *pk = v; }
;         }
.LBB0_364:
	s_or_b64 exec, exec, s[8:9]
	v_mov_b32_e32 v1, v218
	s_barrier
	s_cmp_lg_u32 s34, 0x100
	s_cbranch_scc1 .Lp4_orig
	v_lshrrev_b32_e32 v2, 6, v218
	v_and_b32_e32 v0, 63, v218
	s_load_dwordx2 s[4:5], s[0:1], 0xc8
	v_readfirstlane_b32 s6, v2
	v_lshlrev_b32_e32 v0, 4, v0
	v_mov_b32_e32 v1, 0
	s_mov_b32 s18, -1
	s_mov_b32 s19, 0xffff
	s_mov_b32 s20, -1
	s_mov_b32 s21, 0
	s_add_i32 s6, s6, s70
	s_lshl_b32 s6, s6, 5
	s_waitcnt lgkmcnt(0)
	s_mul_i32 s7, s6, 0x300
	s_add_u32 s8, s4, 0x2c000000
	s_addc_u32 s9, s5, 0
	s_add_u32 s8, s8, s7
	s_addc_u32 s9, s9, 0
	s_lshl_b32 s7, s6, 9
	s_add_u32 s10, s4, 0x2f000000
	s_addc_u32 s11, s5, 0
	s_add_u32 s10, s10, s7
	s_addc_u32 s11, s11, 0
	s_lshl_b32 s7, s6, 2
	s_add_u32 s14, s4, s7
	s_addc_u32 s15, s5, 0
	s_add_u32 s14, s14, 0x40000
	s_addc_u32 s15, s15, 0
	s_add_u32 s16, s14, 0x40000
	s_addc_u32 s17, s15, 0
	s_mov_b32 s22, 8
.Lp4_loop:
	global_load_dword v2, v1, s[14:15]
	global_load_dword v3, v1, s[14:15] offset:4
	global_load_dword v4, v1, s[14:15] offset:8
	global_load_dword v5, v1, s[14:15] offset:12
	global_load_dword v6, v1, s[16:17]
	global_load_dword v7, v1, s[16:17] offset:4
	global_load_dword v8, v1, s[16:17] offset:8
	global_load_dword v9, v1, s[16:17] offset:12
	s_mov_b64 exec, s[18:19]
	global_load_dwordx4 v[40:43], v0, s[8:9]
	global_load_dwordx4 v[44:47], v0, s[8:9] offset:768
	global_load_dwordx4 v[48:51], v0, s[8:9] offset:1536
	global_load_dwordx4 v[52:55], v0, s[8:9] offset:2304
	s_mov_b64 exec, s[20:21]
	global_load_dwordx4 v[56:59], v0, s[10:11]
	global_load_dwordx4 v[60:63], v0, s[10:11] offset:512
	global_load_dwordx4 v[64:67], v0, s[10:11] offset:1024
	global_load_dwordx4 v[18:21], v0, s[10:11] offset:1536
	s_mov_b64 exec, -1
	v_mov_b32_e32 v22, 0x358637bd
	s_waitcnt vmcnt(8)
	v_fmamk_f32 v2, v2, 0x3b2aaaab, v22
	v_fmamk_f32 v3, v3, 0x3b2aaaab, v22
	v_fmamk_f32 v4, v4, 0x3b2aaaab, v22
	v_fmamk_f32 v5, v5, 0x3b2aaaab, v22
	v_fmamk_f32 v6, v6, 0x3b800000, v22
	v_fmamk_f32 v7, v7, 0x3b800000, v22
	v_fmamk_f32 v8, v8, 0x3b800000, v22
	v_fmamk_f32 v9, v9, 0x3b800000, v22
	v_rsq_f32_e32 v2, v2
	v_rsq_f32_e32 v3, v3
	v_rsq_f32_e32 v4, v4
	v_rsq_f32_e32 v5, v5
	v_rsq_f32_e32 v6, v6
	v_rsq_f32_e32 v7, v7
	v_rsq_f32_e32 v8, v8
	v_rsq_f32_e32 v9, v9
	s_nop 0
	s_waitcnt vmcnt(7)
	v_lshlrev_b32_e32 v10, 16, v40
	v_and_b32_e32 v11, 0xffff0000, v40
	v_lshlrev_b32_e32 v12, 16, v41
	v_and_b32_e32 v13, 0xffff0000, v41
	v_lshlrev_b32_e32 v14, 16, v42
	v_and_b32_e32 v15, 0xffff0000, v42
	v_lshlrev_b32_e32 v16, 16, v43
	v_and_b32_e32 v17, 0xffff0000, v43
	v_mul_f32_e32 v10, v2, v10
	v_mul_f32_e32 v11, v2, v11
	v_mul_f32_e32 v12, v2, v12
	v_mul_f32_e32 v13, v2, v13
	v_mul_f32_e32 v14, v2, v14
	v_mul_f32_e32 v15, v2, v15
	v_mul_f32_e32 v16, v2, v16
	v_mul_f32_e32 v17, v2, v17
	v_cvt_pk_bf16_f32 v40, v10, v11
	v_cvt_pk_bf16_f32 v41, v12, v13
	v_cvt_pk_bf16_f32 v42, v14, v15
	v_cvt_pk_bf16_f32 v43, v16, v17
	s_waitcnt vmcnt(6)
	v_lshlrev_b32_e32 v10, 16, v44
	v_and_b32_e32 v11, 0xffff0000, v44
	v_lshlrev_b32_e32 v12, 16, v45
	v_and_b32_e32 v13, 0xffff0000, v45
	v_lshlrev_b32_e32 v14, 16, v46
	v_and_b32_e32 v15, 0xffff0000, v46
	v_lshlrev_b32_e32 v16, 16, v47
	v_and_b32_e32 v17, 0xffff0000, v47
	v_mul_f32_e32 v10, v3, v10
	v_mul_f32_e32 v11, v3, v11
	v_mul_f32_e32 v12, v3, v12
	v_mul_f32_e32 v13, v3, v13
	v_mul_f32_e32 v14, v3, v14
	v_mul_f32_e32 v15, v3, v15
	v_mul_f32_e32 v16, v3, v16
	v_mul_f32_e32 v17, v3, v17
	v_cvt_pk_bf16_f32 v44, v10, v11
	v_cvt_pk_bf16_f32 v45, v12, v13
	v_cvt_pk_bf16_f32 v46, v14, v15
	v_cvt_pk_bf16_f32 v47, v16, v17
	s_waitcnt vmcnt(5)
	v_lshlrev_b32_e32 v10, 16, v48
	v_and_b32_e32 v11, 0xffff0000, v48
	v_lshlrev_b32_e32 v12, 16, v49
	v_and_b32_e32 v13, 0xffff0000, v49
	v_lshlrev_b32_e32 v14, 16, v50
	v_and_b32_e32 v15, 0xffff0000, v50
	v_lshlrev_b32_e32 v16, 16, v51
	v_and_b32_e32 v17, 0xffff0000, v51
	v_mul_f32_e32 v10, v4, v10
	v_mul_f32_e32 v11, v4, v11
	v_mul_f32_e32 v12, v4, v12
	v_mul_f32_e32 v13, v4, v13
	v_mul_f32_e32 v14, v4, v14
	v_mul_f32_e32 v15, v4, v15
	v_mul_f32_e32 v16, v4, v16
	v_mul_f32_e32 v17, v4, v17
	v_cvt_pk_bf16_f32 v48, v10, v11
	v_cvt_pk_bf16_f32 v49, v12, v13
	v_cvt_pk_bf16_f32 v50, v14, v15
	v_cvt_pk_bf16_f32 v51, v16, v17
	s_waitcnt vmcnt(4)
	v_lshlrev_b32_e32 v10, 16, v52
	v_and_b32_e32 v11, 0xffff0000, v52
	v_lshlrev_b32_e32 v12, 16, v53
	v_and_b32_e32 v13, 0xffff0000, v53
	v_lshlrev_b32_e32 v14, 16, v54
	v_and_b32_e32 v15, 0xffff0000, v54
	v_lshlrev_b32_e32 v16, 16, v55
	v_and_b32_e32 v17, 0xffff0000, v55
	v_mul_f32_e32 v10, v5, v10
	v_mul_f32_e32 v11, v5, v11
	v_mul_f32_e32 v12, v5, v12
	v_mul_f32_e32 v13, v5, v13
	v_mul_f32_e32 v14, v5, v14
	v_mul_f32_e32 v15, v5, v15
	v_mul_f32_e32 v16, v5, v16
	v_mul_f32_e32 v17, v5, v17
	v_cvt_pk_bf16_f32 v52, v10, v11
	v_cvt_pk_bf16_f32 v53, v12, v13
	v_cvt_pk_bf16_f32 v54, v14, v15
	v_cvt_pk_bf16_f32 v55, v16, v17
	s_waitcnt vmcnt(3)
; __device__ __forceinline__ unsigned pk2(float lo, float hi) { return pg8::cvt_pk_bf16(lo, hi); }
; __global__ void __launch_bounds__(512, 2) fwd_megakernel(Params p) {
;     ...
;             if (lane < 48) { u32x4* pq = (u32x4*)(cqg + (size_t)m * 384) + lane; u32x4 v = *pq;
; #pragma unroll
;                 for (int q = 0; q < 4; ++q) v[q] = pk2(__uint_as_float(v[q] << 16) * rq, __uint_as_float(v[q] & 0xffff0000u) * rq);
;                 *pq = v; }
;             if (lane < 32) { u32x4* pk = (u32x4*)(ckvg + (size_t)m * 256) + lane; u32x4 v = *pk;
; #pragma unroll
;                 for (int q = 0; q < 4; ++q) v[q] = pk2(__uint_as_float(v[q] << 16) * rk, __uint_as_float(v[q] & 0xffff0000u) * rk);
;                 *pk = v; }
	v_lshlrev_b32_e32 v10, 16, v56
	v_and_b32_e32 v11, 0xffff0000, v56
	v_lshlrev_b32_e32 v12, 16, v57
	v_and_b32_e32 v13, 0xffff0000, v57
	v_lshlrev_b32_e32 v14, 16, v58
	v_and_b32_e32 v15, 0xffff0000, v58
	v_lshlrev_b32_e32 v16, 16, v59
	v_and_b32_e32 v17, 0xffff0000, v59
	v_mul_f32_e32 v10, v6, v10
	v_mul_f32_e32 v11, v6, v11
	v_mul_f32_e32 v12, v6, v12
	v_mul_f32_e32 v13, v6, v13
	v_mul_f32_e32 v14, v6, v14
	v_mul_f32_e32 v15, v6, v15
	v_mul_f32_e32 v16, v6, v16
	v_mul_f32_e32 v17, v6, v17
	v_cvt_pk_bf16_f32 v56, v10, v11
	v_cvt_pk_bf16_f32 v57, v12, v13
	v_cvt_pk_bf16_f32 v58, v14, v15
	v_cvt_pk_bf16_f32 v59, v16, v17
	s_waitcnt vmcnt(2)
	v_lshlrev_b32_e32 v10, 16, v60
	v_and_b32_e32 v11, 0xffff0000, v60
	v_lshlrev_b32_e32 v12, 16, v61
	v_and_b32_e32 v13, 0xffff0000, v61
	v_lshlrev_b32_e32 v14, 16, v62
	v_and_b32_e32 v15, 0xffff0000, v62
	v_lshlrev_b32_e32 v16, 16, v63
	v_and_b32_e32 v17, 0xffff0000, v63
	v_mul_f32_e32 v10, v7, v10
	v_mul_f32_e32 v11, v7, v11
	v_mul_f32_e32 v12, v7, v12
	v_mul_f32_e32 v13, v7, v13
	v_mul_f32_e32 v14, v7, v14
	v_mul_f32_e32 v15, v7, v15
	v_mul_f32_e32 v16, v7, v16
	v_mul_f32_e32 v17, v7, v17
	v_cvt_pk_bf16_f32 v60, v10, v11
	v_cvt_pk_bf16_f32 v61, v12, v13
	v_cvt_pk_bf16_f32 v62, v14, v15
	v_cvt_pk_bf16_f32 v63, v16, v17
	s_waitcnt vmcnt(1)
	v_lshlrev_b32_e32 v10, 16, v64
	v_and_b32_e32 v11, 0xffff0000, v64
	v_lshlrev_b32_e32 v12, 16, v65
	v_and_b32_e32 v13, 0xffff0000, v65
	v_lshlrev_b32_e32 v14, 16, v66
	v_and_b32_e32 v15, 0xffff0000, v66
	v_lshlrev_b32_e32 v16, 16, v67
	v_and_b32_e32 v17, 0xffff0000, v67
	v_mul_f32_e32 v10, v8, v10
	v_mul_f32_e32 v11, v8, v11
	v_mul_f32_e32 v12, v8, v12
	v_mul_f32_e32 v13, v8, v13
	v_mul_f32_e32 v14, v8, v14
	v_mul_f32_e32 v15, v8, v15
	v_mul_f32_e32 v16, v8, v16
	v_mul_f32_e32 v17, v8, v17
	v_cvt_pk_bf16_f32 v64, v10, v11
	v_cvt_pk_bf16_f32 v65, v12, v13
	v_cvt_pk_bf16_f32 v66, v14, v15
	v_cvt_pk_bf16_f32 v67, v16, v17
	s_waitcnt vmcnt(0)
	v_lshlrev_b32_e32 v10, 16, v18
	v_and_b32_e32 v11, 0xffff0000, v18
	v_lshlrev_b32_e32 v12, 16, v19
	v_and_b32_e32 v13, 0xffff0000, v19
	v_lshlrev_b32_e32 v14, 16, v20
	v_and_b32_e32 v15, 0xffff0000, v20
	v_lshlrev_b32_e32 v16, 16, v21
	v_and_b32_e32 v17, 0xffff0000, v21
	v_mul_f32_e32 v10, v9, v10
	v_mul_f32_e32 v11, v9, v11
	v_mul_f32_e32 v12, v9, v12
	v_mul_f32_e32 v13, v9, v13
	v_mul_f32_e32 v14, v9, v14
	v_mul_f32_e32 v15, v9, v15
	v_mul_f32_e32 v16, v9, v16
	v_mul_f32_e32 v17, v9, v17
	v_cvt_pk_bf16_f32 v18, v10, v11
	v_cvt_pk_bf16_f32 v19, v12, v13
	v_cvt_pk_bf16_f32 v20, v14, v15
	v_cvt_pk_bf16_f32 v21, v16, v17
	s_mov_b64 exec, s[18:19]
	global_store_dwordx4 v0, v[40:43], s[8:9]
	global_store_dwordx4 v0, v[44:47], s[8:9] offset:768
	global_store_dwordx4 v0, v[48:51], s[8:9] offset:1536
	global_store_dwordx4 v0, v[52:55], s[8:9] offset:2304
	s_mov_b64 exec, s[20:21]
	global_store_dwordx4 v0, v[56:59], s[10:11]
	global_store_dwordx4 v0, v[60:63], s[10:11] offset:512
	global_store_dwordx4 v0, v[64:67], s[10:11] offset:1024
	global_store_dwordx4 v0, v[18:21], s[10:11] offset:1536
	s_mov_b64 exec, -1
	s_add_u32 s8, s8, 0xc00
	s_addc_u32 s9, s9, 0
	s_add_u32 s10, s10, 0x800
	s_addc_u32 s11, s11, 0
	s_add_u32 s14, s14, 16
	s_addc_u32 s15, s15, 0
	s_add_u32 s16, s16, 16
	s_addc_u32 s17, s17, 0
	s_sub_u32 s22, s22, 1
	s_cmp_lg_u32 s22, 0
	s_cbranch_scc1 .Lp4_loop
	s_branch .Lp4_done
.Lp4_orig:
	s_mov_b32 s3, 0x10000
	v_ashrrev_i32_e32 v0, 6, v1
	v_add_u32_e32 v6, s70, v0
	v_cmp_gt_i32_e32 vcc, s3, v6
	s_and_saveexec_b64 s[12:13], vcc
	s_cbranch_execz .LBB0_371
	v_and_b32_e32 v7, 63, v1
	v_ashrrev_i32_e32 v1, 31, v0
	s_ashr_i32 s71, s70, 31
	v_lshl_add_u64 v[4:5], v[0:1], 0, s[70:71]
	v_lshlrev_b64 v[2:3], 9, v[4:5]
	v_lshlrev_b32_e32 v8, 4, v7
	v_mov_b32_e32 v9, 0
	v_lshl_add_u64 v[2:3], v[2:3], 0, v[8:9]
	s_mov_b64 s[4:5], 0x2f000000
	s_movk_i32 s3, 0x300
	v_lshl_add_u64 v[2:3], v[2:3], 0, s[4:5]
	v_mad_u64_u32 v[8:9], s[4:5], v4, s3, v[8:9]
	v_mov_b64_e32 v[0:1], 0x40000
	s_ashr_i32 s29, s28, 31
	v_mad_i32_i24 v9, v5, s3, v9
	s_mov_b64 s[4:5], 0x2c000000
	v_cmp_gt_u32_e64 s[8:9], 48, v7
	v_cmp_gt_u32_e64 s[10:11], 32, v7
	v_lshl_add_u64 v[0:1], v[4:5], 2, v[0:1]
	s_lshl_b64 s[14:15], s[28:29], 2
	s_lshl_b64 s[16:17], s[28:29], 9
	v_lshl_add_u64 v[4:5], v[8:9], 0, s[4:5]
	s_mul_hi_i32 s19, s28, 0x300
	s_mul_i32 s18, s28, 0x300
	s_mov_b64 s[20:21], 0
	v_mov_b32_e32 v7, 0x358637bd
	s_mov_b32 s3, 0x800000
	s_mov_b32 s4, 0xffff
	s_branch .LBB0_367

; #define LAS __attribute__((address_space(3)))
; __device__ __forceinline__ void hg_prepass(LAS unsigned char* lds, bf16_t* QF, const float* lbtab, bf16_t* P, float* Dg, int G, int bid) {
;     int tid_l = threadIdx.x; asm volatile("" : "+v"(tid_l));
;     const int tid = tid_l, wave = tid >> 6, lane = tid & 63, k = tid & 127, tq = tid >> 7, fr = lane & 15, fq = lane >> 4;
;     constexpr int PP_BUF = 2048 + 2 * 32 * 136 * 2;
;     bf16_t nqr[8], nfr[8];
;     if (bid < 16384) { const int h = bid & 7, bc = bid >> 3; const bf16_t* qp = QF + (size_t)(bc * 32 + 8 * tq) * 2048 + 128 * h + k;
; #pragma unroll
;         for (int j = 0; j < 8; ++j) { nqr[j] = qp[(size_t)j * 2048]; nfr[j] = qp[(size_t)j * 2048 + 1024]; } }
;     int it = 0, hprev = -1; float lb = 0.f, omlb = 0.f;
;     for (int u = bid; u < 16384; u += G, ++it) {
;         LAS float* seg = (LAS float*)(lds + (it & 1) * PP_BUF);
;         LAS bf16_t* Qs = (LAS bf16_t*)(lds + (it & 1) * PP_BUF + 2048);
;         LAS bf16_t* Ks = Qs + 32 * 136;
;         const int h = u & 7, bc = u >> 3, r0 = bc * 32;
.Lp4_done:
	s_mov_b64 s[12:13], s[0:1]
	s_mov_b64 s[8:9], s[0:1]
	s_mov_b64 s[10:11], s[0:1]
	s_mov_b64 s[14:15], s[0:1]
	v_mov_b32_e32 v1, v218
	s_cmpk_gt_i32 s2, 0x3fff
	s_cbranch_scc1 .LBB0_382
	s_load_dwordx2 s[4:5], s[12:13], 0xc8
	s_load_dwordx2 s[6:7], s[14:15], 0xc8
	v_ashrrev_i32_e32 v24, 7, v1
	v_lshlrev_b32_e32 v2, 3, v24
	v_and_b32_e32 v0, 0x7f, v1
	s_waitcnt lgkmcnt(0)
	s_add_u32 s40, s4, 0x1c000000
	s_addc_u32 s41, s5, 0
	s_add_u32 s4, s6, 0x6000000
	s_addc_u32 s5, s7, 0
	s_lshl_b32 s3, s2, 2
	s_andn2_b32 s3, s3, 31
	v_add_u32_e32 v4, s3, v2
	v_ashrrev_i32_e32 v5, 31, v4
	v_lshlrev_b64 v[4:5], 12, v[4:5]
	s_lshl_b32 s3, s2, 8
	v_lshl_add_u64 v[4:5], s[40:41], 0, v[4:5]
	s_and_b32 s42, s3, 0x700
	s_mov_b32 s43, 0
	v_lshl_add_u64 v[6:7], v[4:5], 0, s[42:43]
	v_mov_b32_e32 v5, 0
	v_lshlrev_b32_e32 v4, 1, v0
	v_lshl_add_u64 v[6:7], v[6:7], 0, v[4:5]
	s_movk_i32 s6, 0x1000
	s_waitcnt vmcnt(0)
	v_add_co_u32_e32 v8, vcc, s6, v6
	s_movk_i32 s7, 0x2000
	s_nop 0
	v_addc_co_u32_e32 v9, vcc, 0, v7, vcc
	v_add_co_u32_e32 v10, vcc, s7, v6
	s_movk_i32 s29, 0x3000
	s_nop 0
	v_addc_co_u32_e32 v11, vcc, 0, v7, vcc
	v_add_co_u32_e32 v12, vcc, s29, v6
	s_movk_i32 s30, 0x4000
	s_nop 0
	v_addc_co_u32_e32 v13, vcc, 0, v7, vcc
	v_add_co_u32_e32 v16, vcc, s30, v6
	s_movk_i32 s3, 0x5000
	s_nop 0
	v_addc_co_u32_e32 v17, vcc, 0, v7, vcc
	v_add_co_u32_e32 v18, vcc, s3, v6
	s_movk_i32 s31, 0x6000
	s_nop 0
	v_addc_co_u32_e32 v19, vcc, 0, v7, vcc
	v_add_co_u32_e32 v22, vcc, s31, v6
	s_movk_i32 s33, 0x7000
	s_nop 0
	v_addc_co_u32_e32 v23, vcc, 0, v7, vcc
	global_load_ushort v39, v[10:11], off
	global_load_ushort v15, v[10:11], off offset:2048
	global_load_ushort v40, v[16:17], off offset:-4096
	global_load_ushort v41, v[16:17], off
	global_load_ushort v20, v[16:17], off offset:2048
	global_load_ushort v42, v[22:23], off offset:-4096
	global_load_ushort v43, v[22:23], off
	global_load_ushort v21, v[22:23], off offset:2048
	v_add_co_u32_e32 v16, vcc, s33, v6
	s_movk_i32 s3, 0x80
	s_nop 0
	v_addc_co_u32_e32 v17, vcc, 0, v7, vcc
	global_load_ushort v49, v[6:7], off
	global_load_ushort v45, v[6:7], off offset:2048
	global_load_ushort v50, v[10:11], off offset:-4096
	global_load_ushort v47, v[8:9], off offset:2048
	global_load_ushort v46, v[12:13], off offset:2048
	global_load_ushort v44, v[18:19], off offset:2048
	global_load_ushort v51, v[16:17], off
	global_load_ushort v48, v[16:17], off offset:2048
	v_ashrrev_i32_e32 v7, 6, v1
	v_cmp_lt_i32_e32 vcc, 0, v7
	v_bfe_u32 v4, v1, 4, 2
	v_and_b32_e32 v6, 15, v1
	v_cndmask_b32_e64 v8, 0, 16, vcc
	v_cmp_eq_u32_e32 vcc, 2, v7
	v_cmp_gt_u32_e64 s[14:15], s3, v1
	v_cmp_gt_i32_e64 s[16:17], 3, v7
	v_cndmask_b32_e64 v7, 0, 16, vcc
	s_movk_i32 s3, 0x440
	v_or_b32_e32 v9, v8, v6
	v_or_b32_e32 v10, v7, v6
	v_lshl_or_b32 v12, v4, 2, v8
	v_mad_u64_u32 v[6:7], s[18:19], v24, s3, v[0:1]
	v_or_b32_e32 v7, 1, v12
	s_load_dwordx2 s[44:45], s[8:9], 0x38
	s_load_dwordx2 s[26:27], s[10:11], 0xc8
	v_cmp_gt_u32_e64 s[20:21], v10, v7
	v_or_b32_e32 v7, 2, v12
	v_cmp_gt_u32_e64 s[22:23], v10, v7
	v_or_b32_e32 v7, 3, v12
	v_lshlrev_b32_e32 v16, 3, v4
	v_cmp_gt_u32_e64 s[24:25], v10, v7
	v_lshlrev_b32_e32 v4, 8, v4
	v_lshlrev_b32_e32 v7, 6, v8
	s_brev_b32 s3, 32
	v_or3_b32 v8, v4, v7, s3
	s_ashr_i32 s3, s2, 31
	s_lshl_b64 s[36:37], s[2:3], 11
	s_waitcnt lgkmcnt(0)
	s_add_u32 s26, s26, s36
	v_lshlrev_b32_e32 v3, 5, v1
	v_lshlrev_b32_e32 v4, 1, v10
	s_addc_u32 s27, s27, s37
	v_and_b32_e32 v14, 0x60, v3
	v_mul_u32_u24_e32 v22, 0x110, v10
	v_cmp_gt_u32_e64 s[18:19], v10, v12
	v_lshl_add_u64 v[10:11], s[26:27], 0, v[4:5]
	s_ashr_i32 s35, s34, 31
	v_mov_b32_e32 v4, 0x4000080
	s_add_i32 s26, s2, s34
	v_cmp_lt_i32_e64 s[8:9], 0, v24
	v_cmp_lt_i32_e64 s[10:11], 1, v24
	v_cmp_lt_i32_e64 s[12:13], 2, v24
	v_bfe_u32 v17, v1, 2, 5
	v_ashrrev_i32_e32 v3, 31, v2
	v_mul_u32_u24_e32 v19, 0x110, v9
	v_mov_b32_e32 v9, v5
	s_lshl_b64 s[46:47], s[34:35], 11
	v_lshl_or_b32 v12, v12, 6, v4
	v_mov_b32_e32 v13, v5
	s_lshl_b32 s3, s26, 2
	s_lshl_b32 s35, s34, 2
	s_lshl_b32 s36, s26, 7
	s_lshl_b32 s37, s34, 7
	s_mov_b32 s54, -1
	s_mov_b64 s[48:49], 0
	v_lshlrev_b32_e32 v4, 1, v0
	s_movk_i32 s38, 0x7fff
	s_mov_b32 s39, 0xffff0000
	v_lshlrev_b32_e32 v14, 1, v14
	v_lshlrev_b32_e32 v7, 1, v16
	v_mov_b32_e32 v16, v5
	v_mov_b32_e32 v18, v5
	s_mov_b32 s50, s2
	s_branch .LBB0_374
